# p12 heavy epilogue: all four lbp load pairs issued at the first column group (one exposed latency instead of four)
# speedup vs baseline: 1.0032x; 1.0032x over previous
; DEV float sigm(float x) { return 1.f / (1.f + __expf(-x)); }
;   DEV void operator()(int m, int n, f32x4 v) {
;     ...
;     if (seg == 1 || seg == 2) {
;       const int dir = seg - 1;
; #pragma unroll
;       for (int r = 0; r < 4; r++) {
;         float lb = sigm(lbp[(2 + dir) * 1024 + c + r] - lbp[dir * 1024 + c + r]);
;         float ff = lb + (1.f - lb) * sigm(v[r]);
;         v[r] = __logf(ff);
;       }
;     }
.LBB0_344:
	v_lshrrev_b32_e32 v0, 2, v140
	v_and_or_b32 v0, v0, 12, s13
	s_movk_i32 s23, 0x3cc
	s_waitcnt vmcnt(6)
	v_bitop3_b32 v79, v0, s23, v142 bitop3:0xc8
	s_and_b32 s23, s13, 0xfffffc00
	v_or_b32_e32 v78, v0, v142
	s_add_i32 s13, s23, 0x400
	v_or_b32_e32 v66, s13, v79
	v_add_u32_e32 v68, 0xfffffc00, v78
	v_ashrrev_i32_e32 v67, 31, v66
	v_ashrrev_i32_e32 v69, 31, v68
	s_andn2_b64 vcc, exec, s[0:1]
	v_lshl_add_u64 v[74:75], v[66:67], 2, s[46:47]
	v_lshl_add_u64 v[76:77], v[68:69], 2, s[46:47]
	s_cbranch_vccnz .LBB0_346
	global_load_dwordx4 v[66:69], v[74:75], off
	global_load_dwordx4 v[70:73], v[76:77], off
	global_load_dwordx4 v[184:187], v[74:75], off offset:64
	global_load_dwordx4 v[188:191], v[76:77], off offset:64
	global_load_dwordx4 v[236:239], v[74:75], off offset:128
	global_load_dwordx4 v[240:243], v[76:77], off offset:128
	global_load_dwordx4 v[244:247], v[74:75], off offset:192
	global_load_dwordx2 v[248:249], v[76:77], off offset:192
	global_load_dwordx2 v[192:193], v[76:77], off offset:200
	s_mov_b32 s34, 0x800000
	s_mov_b32 s13, 0x7f800000
	s_waitcnt vmcnt(0)
	v_mov_b32_e32 v84, v66
	v_mov_b32_e32 v85, v67
	v_mov_b32_e32 v86, v68
	v_mov_b32_e32 v87, v69
	v_mov_b32_e32 v88, v70
	v_mov_b32_e32 v89, v71
	v_mov_b32_e32 v90, v72
	v_mov_b32_e32 v91, v73
	v_sub_f32_e32 v0, v66, v70
	v_mul_f32_e32 v0, 0xbfb8aa3b, v0
	v_exp_f32_e32 v80, v0
	v_mul_f32_e32 v0, 0xbfb8aa3b, v62
	v_exp_f32_e32 v81, v0
	s_nop 0
	v_pk_add_f32 v[80:81], v[80:81], 1.0 op_sel_hi:[1,0]
	s_nop 0
	v_div_scale_f32 v0, s[0:1], v81, v81, 1.0
	v_rcp_f32_e32 v62, v0
	s_nop 0
	v_fma_f32 v66, -v0, v62, 1.0
	v_fmac_f32_e32 v62, v66, v62
	v_div_scale_f32 v66, vcc, 1.0, v81, 1.0
	v_mul_f32_e32 v70, v66, v62
	v_fma_f32 v82, -v0, v70, v66
	v_fmac_f32_e32 v70, v82, v62
	v_fma_f32 v0, -v0, v70, v66
	v_div_fmas_f32 v0, v0, v62, v70
	v_div_scale_f32 v62, s[0:1], v80, v80, 1.0
	v_rcp_f32_e32 v66, v62
	v_div_fixup_f32 v0, v0, v81, 1.0
	v_fma_f32 v70, -v62, v66, 1.0
	v_fmac_f32_e32 v66, v70, v66
	v_div_scale_f32 v70, vcc, 1.0, v80, 1.0
	v_mul_f32_e32 v81, v70, v66
	v_fma_f32 v82, -v62, v81, v70
	v_fmac_f32_e32 v81, v82, v66
	v_fma_f32 v62, -v62, v81, v70
	v_div_fmas_f32 v62, v62, v66, v81
	v_div_fixup_f32 v62, v62, v80, 1.0
	v_sub_f32_e32 v66, 1.0, v62
	v_fmac_f32_e32 v62, v0, v66
	v_cmp_gt_f32_e32 vcc, s34, v62
	s_nop 1
	v_cndmask_b32_e64 v0, 0, 32, vcc
	v_ldexp_f32 v0, v62, v0
	v_log_f32_e32 v0, v0
	s_nop 0
	v_mul_f32_e32 v62, 0x3f317217, v0
	v_fma_f32 v62, v0, s37, -v62
	v_fmac_f32_e32 v62, 0x3377d1cf, v0
	v_fmac_f32_e32 v62, 0x3f317217, v0
	v_cmp_lt_f32_e64 s[38:39], |v0|, s13
	s_nop 1
	v_cndmask_b32_e64 v0, v0, v62, s[38:39]
	v_cndmask_b32_e32 v62, 0, v225, vcc
	v_sub_f32_e32 v62, v0, v62
	v_sub_f32_e32 v0, v67, v71
	v_mul_f32_e32 v0, 0xbfb8aa3b, v0
	v_exp_f32_e32 v66, v0
	v_mul_f32_e32 v0, 0xbfb8aa3b, v63
	v_exp_f32_e32 v67, v0
	s_nop 0
	v_pk_add_f32 v[66:67], v[66:67], 1.0 op_sel_hi:[1,0]
	s_nop 0
	v_div_scale_f32 v0, s[0:1], v67, v67, 1.0
	v_rcp_f32_e32 v63, v0
	s_nop 0
	v_fma_f32 v70, -v0, v63, 1.0
	v_fmac_f32_e32 v63, v70, v63
	v_div_scale_f32 v70, vcc, 1.0, v67, 1.0
	v_mul_f32_e32 v71, v70, v63
	v_fma_f32 v80, -v0, v71, v70
	v_fmac_f32_e32 v71, v80, v63
	v_fma_f32 v0, -v0, v71, v70
	v_div_fmas_f32 v0, v0, v63, v71
	v_div_scale_f32 v63, s[0:1], v66, v66, 1.0
	v_div_fixup_f32 v0, v0, v67, 1.0
	v_rcp_f32_e32 v67, v63
	s_nop 0
	v_fma_f32 v70, -v63, v67, 1.0
	v_fmac_f32_e32 v67, v70, v67
	v_div_scale_f32 v70, vcc, 1.0, v66, 1.0
	v_mul_f32_e32 v71, v70, v67
	v_fma_f32 v80, -v63, v71, v70
	v_fmac_f32_e32 v71, v80, v67
	v_fma_f32 v63, -v63, v71, v70
	v_div_fmas_f32 v63, v63, v67, v71
	v_div_fixup_f32 v63, v63, v66, 1.0
	v_sub_f32_e32 v66, 1.0, v63
	v_fmac_f32_e32 v63, v0, v66
	v_cmp_gt_f32_e32 vcc, s34, v63
	s_nop 1
	v_cndmask_b32_e64 v0, 0, 32, vcc
	v_ldexp_f32 v0, v63, v0
	v_log_f32_e32 v0, v0
	s_nop 0
	v_mul_f32_e32 v63, 0x3f317217, v0
	v_fma_f32 v63, v0, s37, -v63
	v_fmac_f32_e32 v63, 0x3377d1cf, v0
	v_fmac_f32_e32 v63, 0x3f317217, v0
	v_cmp_lt_f32_e64 s[38:39], |v0|, s13
	s_nop 1
	v_cndmask_b32_e64 v0, v0, v63, s[38:39]
	v_cndmask_b32_e32 v63, 0, v225, vcc
	v_sub_f32_e32 v63, v0, v63
	v_sub_f32_e32 v0, v68, v72
	v_mul_f32_e32 v0, 0xbfb8aa3b, v0
	v_exp_f32_e32 v66, v0
	v_mul_f32_e32 v0, 0xbfb8aa3b, v64
	v_exp_f32_e32 v67, v0
	s_nop 0
	v_pk_add_f32 v[66:67], v[66:67], 1.0 op_sel_hi:[1,0]
	s_nop 0
	v_div_scale_f32 v0, s[0:1], v67, v67, 1.0
	v_rcp_f32_e32 v64, v0
	s_nop 0
	v_fma_f32 v68, -v0, v64, 1.0
	v_fmac_f32_e32 v64, v68, v64
	v_div_scale_f32 v68, vcc, 1.0, v67, 1.0
	v_mul_f32_e32 v70, v68, v64
	v_fma_f32 v71, -v0, v70, v68
	v_fmac_f32_e32 v70, v71, v64
	v_fma_f32 v0, -v0, v70, v68
	v_div_fmas_f32 v0, v0, v64, v70
	v_div_scale_f32 v64, s[0:1], v66, v66, 1.0
	v_div_fixup_f32 v0, v0, v67, 1.0
	v_rcp_f32_e32 v67, v64
	s_nop 0
	v_fma_f32 v68, -v64, v67, 1.0
	v_fmac_f32_e32 v67, v68, v67
	v_div_scale_f32 v68, vcc, 1.0, v66, 1.0
	v_mul_f32_e32 v70, v68, v67
	v_fma_f32 v71, -v64, v70, v68
	v_fmac_f32_e32 v70, v71, v67
	v_fma_f32 v64, -v64, v70, v68
	v_div_fmas_f32 v64, v64, v67, v70
	v_div_fixup_f32 v64, v64, v66, 1.0
	v_sub_f32_e32 v66, 1.0, v64
	v_fmac_f32_e32 v64, v0, v66
	v_cmp_gt_f32_e32 vcc, s34, v64
	s_nop 1
	v_cndmask_b32_e64 v0, 0, 32, vcc
	v_ldexp_f32 v0, v64, v0
	v_log_f32_e32 v0, v0
	s_nop 0
	v_mul_f32_e32 v64, 0x3f317217, v0
	v_fma_f32 v64, v0, s37, -v64
	v_fmac_f32_e32 v64, 0x3377d1cf, v0
	v_fmac_f32_e32 v64, 0x3f317217, v0
	v_cmp_lt_f32_e64 s[38:39], |v0|, s13
	s_nop 1
	v_cndmask_b32_e64 v0, v0, v64, s[38:39]
	v_cndmask_b32_e32 v64, 0, v225, vcc
	v_sub_f32_e32 v64, v0, v64
	v_sub_f32_e32 v0, v69, v73
	v_mul_f32_e32 v0, 0xbfb8aa3b, v0
	v_exp_f32_e32 v66, v0
	v_mul_f32_e32 v0, 0xbfb8aa3b, v65
	v_exp_f32_e32 v67, v0
	s_nop 0
	v_pk_add_f32 v[66:67], v[66:67], 1.0 op_sel_hi:[1,0]
	s_nop 0
	v_div_scale_f32 v0, s[0:1], v67, v67, 1.0
	v_rcp_f32_e32 v65, v0
	s_nop 0
	v_fma_f32 v68, -v0, v65, 1.0
	v_fmac_f32_e32 v65, v68, v65
	v_div_scale_f32 v68, vcc, 1.0, v67, 1.0
	v_mul_f32_e32 v69, v68, v65
	v_fma_f32 v70, -v0, v69, v68
	v_fmac_f32_e32 v69, v70, v65
	v_fma_f32 v0, -v0, v69, v68
	v_div_fmas_f32 v0, v0, v65, v69
	v_div_scale_f32 v65, s[0:1], v66, v66, 1.0
	v_div_fixup_f32 v0, v0, v67, 1.0
	v_rcp_f32_e32 v67, v65
	s_nop 0
	v_fma_f32 v68, -v65, v67, 1.0
	v_fmac_f32_e32 v67, v68, v67
	v_div_scale_f32 v68, vcc, 1.0, v66, 1.0
	v_mul_f32_e32 v69, v68, v67
	v_fma_f32 v70, -v65, v69, v68
	v_fmac_f32_e32 v69, v70, v67
	v_fma_f32 v65, -v65, v69, v68
	v_div_fmas_f32 v65, v65, v67, v69
	v_div_fixup_f32 v65, v65, v66, 1.0
	v_sub_f32_e32 v66, 1.0, v65
	v_fmac_f32_e32 v65, v0, v66
	v_cmp_gt_f32_e32 vcc, s34, v65
	s_mov_b64 s[34:35], 0x100
	s_nop 0
	v_cndmask_b32_e64 v0, 0, 32, vcc
	v_ldexp_f32 v0, v65, v0
	v_log_f32_e32 v0, v0
	s_nop 0
	v_mul_f32_e32 v65, 0x3f317217, v0
	v_fma_f32 v65, v0, s37, -v65
	v_fmac_f32_e32 v65, 0x3377d1cf, v0
	v_fmac_f32_e32 v65, 0x3f317217, v0
	v_cmp_lt_f32_e64 s[38:39], |v0|, s13
	s_nop 1
	v_cndmask_b32_e64 v0, v0, v65, s[38:39]
	v_cndmask_b32_e32 v65, 0, v225, vcc
	v_sub_f32_e32 v65, v0, v65

; DEV float sigm(float x) { return 1.f / (1.f + __expf(-x)); }
;   DEV void operator()(int m, int n, f32x4 v) {
;     ...
;     if (seg == 1 || seg == 2) {
;       const int dir = seg - 1;
; #pragma unroll
;       for (int r = 0; r < 4; r++) {
;         float lb = sigm(lbp[(2 + dir) * 1024 + c + r] - lbp[dir * 1024 + c + r]);
;         float ff = lb + (1.f - lb) * sigm(v[r]);
;         v[r] = __logf(ff);
;       }
;     }
.LBB0_412:
	s_add_i32 s10, s23, 0x410
	v_or_b32_e32 v50, s10, v79
	v_add_u32_e32 v52, 0xfffffc10, v78
	v_ashrrev_i32_e32 v51, 31, v50
	v_ashrrev_i32_e32 v53, 31, v52
	s_andn2_b64 vcc, exec, s[0:1]
	v_lshl_add_u64 v[60:61], v[50:51], 2, s[46:47]
	v_lshl_add_u64 v[64:65], v[52:53], 2, s[46:47]
	s_cbranch_vccnz .LBB0_414
	v_mul_f32_e32 v46, 0xbfb8aa3b, v46
	v_exp_f32_e32 v69, v46
	s_mov_b32 s11, 0x800000
	s_mov_b32 s10, 0x7f800000
	v_mul_f32_e32 v47, 0xbfb8aa3b, v47
	v_mul_f32_e32 v48, 0xbfb8aa3b, v48
	v_mul_f32_e32 v49, 0xbfb8aa3b, v49
	v_mov_b32_e32 v50, v184
	v_mov_b32_e32 v51, v185
	v_mov_b32_e32 v52, v186
	v_mov_b32_e32 v53, v187
	v_mov_b32_e32 v54, v188
	v_mov_b32_e32 v55, v189
	v_mov_b32_e32 v56, v190
	v_mov_b32_e32 v57, v191
	v_mov_b32_e32 v84, v50
	v_mov_b32_e32 v85, v51
	v_mov_b32_e32 v86, v52
	v_mov_b32_e32 v87, v53
	v_mov_b32_e32 v88, v54
	v_mov_b32_e32 v89, v55
	v_mov_b32_e32 v90, v56
	v_mov_b32_e32 v91, v57
	v_sub_f32_e32 v50, v50, v54
	v_mul_f32_e32 v50, 0xbfb8aa3b, v50
	v_exp_f32_e32 v68, v50
	s_nop 0
	v_pk_add_f32 v[68:69], v[68:69], 1.0 op_sel_hi:[1,0]
	s_nop 0
	v_div_scale_f32 v46, s[0:1], v69, v69, 1.0
	v_rcp_f32_e32 v50, v46
	s_nop 0
	v_fma_f32 v54, -v46, v50, 1.0
	v_fmac_f32_e32 v50, v54, v50
	v_div_scale_f32 v54, vcc, 1.0, v69, 1.0
	v_mul_f32_e32 v72, v54, v50
	v_fma_f32 v73, -v46, v72, v54
	v_fmac_f32_e32 v72, v73, v50
	v_fma_f32 v46, -v46, v72, v54
	v_div_fmas_f32 v46, v46, v50, v72
	v_div_scale_f32 v50, s[0:1], v68, v68, 1.0
	v_rcp_f32_e32 v54, v50
	v_div_fixup_f32 v46, v46, v69, 1.0
	v_fma_f32 v69, -v50, v54, 1.0
	v_fmac_f32_e32 v54, v69, v54
	v_div_scale_f32 v69, vcc, 1.0, v68, 1.0
	v_mul_f32_e32 v72, v69, v54
	v_fma_f32 v73, -v50, v72, v69
	v_fmac_f32_e32 v72, v73, v54
	v_fma_f32 v50, -v50, v72, v69
	v_div_fmas_f32 v50, v50, v54, v72
	v_div_fixup_f32 v50, v50, v68, 1.0
	v_sub_f32_e32 v54, 1.0, v50
	v_fmac_f32_e32 v50, v46, v54
	v_cmp_gt_f32_e32 vcc, s11, v50
	s_nop 1
	v_cndmask_b32_e64 v46, 0, 32, vcc
	v_ldexp_f32 v46, v50, v46
	v_log_f32_e32 v46, v46
	s_nop 0
	v_mul_f32_e32 v50, 0x3f317217, v46
	v_fma_f32 v50, v46, s37, -v50
	v_fmac_f32_e32 v50, 0x3377d1cf, v46
	v_fmac_f32_e32 v50, 0x3f317217, v46
	v_cmp_lt_f32_e64 s[42:43], |v46|, s10
	s_nop 1
	v_cndmask_b32_e64 v46, v46, v50, s[42:43]
	v_cndmask_b32_e32 v50, 0, v225, vcc
	v_sub_f32_e32 v46, v46, v50
	v_sub_f32_e32 v50, v51, v55
	v_mul_f32_e32 v50, 0xbfb8aa3b, v50
	v_exp_f32_e32 v50, v50
	v_exp_f32_e32 v51, v47
	s_nop 0
	v_pk_add_f32 v[50:51], v[50:51], 1.0 op_sel_hi:[1,0]
	s_nop 0
	v_div_scale_f32 v47, s[0:1], v51, v51, 1.0
	v_rcp_f32_e32 v54, v47
	s_nop 0
	v_fma_f32 v55, -v47, v54, 1.0
	v_fmac_f32_e32 v54, v55, v54
	v_div_scale_f32 v55, vcc, 1.0, v51, 1.0
	v_mul_f32_e32 v68, v55, v54
	v_fma_f32 v69, -v47, v68, v55
	v_fmac_f32_e32 v68, v69, v54
	v_fma_f32 v47, -v47, v68, v55
	v_div_fmas_f32 v47, v47, v54, v68
	v_div_fixup_f32 v47, v47, v51, 1.0
	v_div_scale_f32 v51, s[0:1], v50, v50, 1.0
	v_rcp_f32_e32 v54, v51
	s_nop 0
	v_fma_f32 v55, -v51, v54, 1.0
	v_fmac_f32_e32 v54, v55, v54
	v_div_scale_f32 v55, vcc, 1.0, v50, 1.0
	v_mul_f32_e32 v68, v55, v54
	v_fma_f32 v69, -v51, v68, v55
	v_fmac_f32_e32 v68, v69, v54
	v_fma_f32 v51, -v51, v68, v55
	v_div_fmas_f32 v51, v51, v54, v68
	v_div_fixup_f32 v50, v51, v50, 1.0
	v_sub_f32_e32 v51, 1.0, v50
	v_fmac_f32_e32 v50, v47, v51
	v_cmp_gt_f32_e32 vcc, s11, v50
	v_exp_f32_e32 v51, v48
	s_nop 0
	v_cndmask_b32_e64 v47, 0, 32, vcc
	v_ldexp_f32 v47, v50, v47
	v_log_f32_e32 v47, v47
	s_nop 0
	v_mul_f32_e32 v50, 0x3f317217, v47
	v_fma_f32 v50, v47, s37, -v50
	v_fmac_f32_e32 v50, 0x3377d1cf, v47
	v_fmac_f32_e32 v50, 0x3f317217, v47
	v_cmp_lt_f32_e64 s[42:43], |v47|, s10
	s_nop 1
	v_cndmask_b32_e64 v47, v47, v50, s[42:43]
	v_cndmask_b32_e32 v50, 0, v225, vcc
	v_sub_f32_e32 v47, v47, v50
	v_sub_f32_e32 v50, v52, v56
	v_mul_f32_e32 v50, 0xbfb8aa3b, v50
	v_exp_f32_e32 v50, v50
	s_nop 0
	v_pk_add_f32 v[50:51], v[50:51], 1.0 op_sel_hi:[1,0]
	s_nop 0
	v_div_scale_f32 v48, s[0:1], v51, v51, 1.0
	v_rcp_f32_e32 v52, v48
	s_nop 0
	v_fma_f32 v54, -v48, v52, 1.0
	v_fmac_f32_e32 v52, v54, v52
	v_div_scale_f32 v54, vcc, 1.0, v51, 1.0
	v_mul_f32_e32 v55, v54, v52
	v_fma_f32 v56, -v48, v55, v54
	v_fmac_f32_e32 v55, v56, v52
	v_fma_f32 v48, -v48, v55, v54
	v_div_fmas_f32 v48, v48, v52, v55
	v_div_fixup_f32 v48, v48, v51, 1.0
	v_div_scale_f32 v51, s[0:1], v50, v50, 1.0
	v_rcp_f32_e32 v52, v51
	s_nop 0
	v_fma_f32 v54, -v51, v52, 1.0
	v_fmac_f32_e32 v52, v54, v52
	v_div_scale_f32 v54, vcc, 1.0, v50, 1.0
	v_mul_f32_e32 v55, v54, v52
	v_fma_f32 v56, -v51, v55, v54
	v_fmac_f32_e32 v55, v56, v52
	v_fma_f32 v51, -v51, v55, v54
	v_div_fmas_f32 v51, v51, v52, v55
	v_div_fixup_f32 v50, v51, v50, 1.0
	v_sub_f32_e32 v51, 1.0, v50
	v_fmac_f32_e32 v50, v48, v51
	v_cmp_gt_f32_e32 vcc, s11, v50
	v_exp_f32_e32 v51, v49
	s_nop 0
	v_cndmask_b32_e64 v48, 0, 32, vcc
	v_ldexp_f32 v48, v50, v48
	v_log_f32_e32 v48, v48
	s_nop 0
	v_mul_f32_e32 v50, 0x3f317217, v48
	v_fma_f32 v50, v48, s37, -v50
	v_fmac_f32_e32 v50, 0x3377d1cf, v48
	v_fmac_f32_e32 v50, 0x3f317217, v48
	v_cmp_lt_f32_e64 s[42:43], |v48|, s10
	s_nop 1
	v_cndmask_b32_e64 v48, v48, v50, s[42:43]
	v_cndmask_b32_e32 v50, 0, v225, vcc
	v_sub_f32_e32 v48, v48, v50
	v_sub_f32_e32 v50, v53, v57
	v_mul_f32_e32 v50, 0xbfb8aa3b, v50
	v_exp_f32_e32 v50, v50
	s_nop 0
	v_pk_add_f32 v[50:51], v[50:51], 1.0 op_sel_hi:[1,0]
	s_nop 0
	v_div_scale_f32 v49, s[0:1], v51, v51, 1.0
	v_rcp_f32_e32 v52, v49
	s_nop 0
	v_fma_f32 v53, -v49, v52, 1.0
	v_fmac_f32_e32 v52, v53, v52
	v_div_scale_f32 v53, vcc, 1.0, v51, 1.0
	v_mul_f32_e32 v54, v53, v52
	v_fma_f32 v55, -v49, v54, v53
	v_fmac_f32_e32 v54, v55, v52
	v_fma_f32 v49, -v49, v54, v53
	v_div_fmas_f32 v49, v49, v52, v54
	v_div_fixup_f32 v49, v49, v51, 1.0
	v_div_scale_f32 v51, s[0:1], v50, v50, 1.0
	v_rcp_f32_e32 v52, v51
	s_nop 0
	v_fma_f32 v53, -v51, v52, 1.0
	v_fmac_f32_e32 v52, v53, v52
	v_div_scale_f32 v53, vcc, 1.0, v50, 1.0
	v_mul_f32_e32 v54, v53, v52
	v_fma_f32 v55, -v51, v54, v53
	v_fmac_f32_e32 v54, v55, v52
	v_fma_f32 v51, -v51, v54, v53
	v_div_fmas_f32 v51, v51, v52, v54
	v_div_fixup_f32 v50, v51, v50, 1.0
	v_sub_f32_e32 v51, 1.0, v50
	v_fmac_f32_e32 v50, v49, v51
	v_cmp_gt_f32_e32 vcc, s11, v50
	s_nop 1
	v_cndmask_b32_e64 v49, 0, 32, vcc
	v_ldexp_f32 v49, v50, v49
	v_log_f32_e32 v49, v49
	s_nop 0
	v_mul_f32_e32 v50, 0x3f317217, v49
	v_fma_f32 v50, v49, s37, -v50
	v_fmac_f32_e32 v50, 0x3377d1cf, v49
	v_fmac_f32_e32 v50, 0x3f317217, v49
	v_cmp_lt_f32_e64 s[42:43], |v49|, s10
	s_nop 1
	v_cndmask_b32_e64 v49, v49, v50, s[42:43]
	v_cndmask_b32_e32 v50, 0, v225, vcc
	v_sub_f32_e32 v49, v49, v50

; DEV float sigm(float x) { return 1.f / (1.f + __expf(-x)); }
;   DEV void operator()(int m, int n, f32x4 v) {
;     ...
;     if (seg == 1 || seg == 2) {
;       const int dir = seg - 1;
; #pragma unroll
;       for (int r = 0; r < 4; r++) {
;         float lb = sigm(lbp[(2 + dir) * 1024 + c + r] - lbp[dir * 1024 + c + r]);
;         float ff = lb + (1.f - lb) * sigm(v[r]);
;         v[r] = __logf(ff);
;       }
;     }
.LBB0_480:
	s_add_i32 s10, s23, 0x420
	v_or_b32_e32 v34, s10, v79
	v_add_u32_e32 v36, 0xfffffc20, v78
	v_ashrrev_i32_e32 v35, 31, v34
	v_ashrrev_i32_e32 v37, 31, v36
	s_andn2_b64 vcc, exec, s[0:1]
	v_lshl_add_u64 v[42:43], v[34:35], 2, s[46:47]
	v_lshl_add_u64 v[44:45], v[36:37], 2, s[46:47]
	s_cbranch_vccnz .LBB0_482
	v_mul_f32_e32 v30, 0xbfb8aa3b, v30
	v_exp_f32_e32 v47, v30
	s_mov_b32 s11, 0x800000
	s_mov_b32 s10, 0x7f800000
	v_mul_f32_e32 v31, 0xbfb8aa3b, v31
	v_mul_f32_e32 v32, 0xbfb8aa3b, v32
	v_mul_f32_e32 v33, 0xbfb8aa3b, v33
	v_mov_b32_e32 v34, v236
	v_mov_b32_e32 v35, v237
	v_mov_b32_e32 v36, v238
	v_mov_b32_e32 v37, v239
	v_mov_b32_e32 v38, v240
	v_mov_b32_e32 v39, v241
	v_mov_b32_e32 v40, v242
	v_mov_b32_e32 v41, v243
	v_mov_b32_e32 v84, v34
	v_mov_b32_e32 v85, v35
	v_mov_b32_e32 v86, v36
	v_mov_b32_e32 v87, v37
	v_mov_b32_e32 v88, v38
	v_mov_b32_e32 v89, v39
	v_mov_b32_e32 v90, v40
	v_mov_b32_e32 v91, v41
	v_sub_f32_e32 v34, v34, v38
	v_mul_f32_e32 v34, 0xbfb8aa3b, v34
	v_exp_f32_e32 v46, v34
	s_nop 0
	v_pk_add_f32 v[46:47], v[46:47], 1.0 op_sel_hi:[1,0]
	s_nop 0
	v_div_scale_f32 v30, s[0:1], v47, v47, 1.0
	v_rcp_f32_e32 v34, v30
	s_nop 0
	v_fma_f32 v38, -v30, v34, 1.0
	v_fmac_f32_e32 v34, v38, v34
	v_div_scale_f32 v38, vcc, 1.0, v47, 1.0
	v_mul_f32_e32 v48, v38, v34
	v_fma_f32 v49, -v30, v48, v38
	v_fmac_f32_e32 v48, v49, v34
	v_fma_f32 v30, -v30, v48, v38
	v_div_fmas_f32 v30, v30, v34, v48
	v_div_scale_f32 v34, s[0:1], v46, v46, 1.0
	v_rcp_f32_e32 v38, v34
	v_div_fixup_f32 v30, v30, v47, 1.0
	v_fma_f32 v47, -v34, v38, 1.0
	v_fmac_f32_e32 v38, v47, v38
	v_div_scale_f32 v47, vcc, 1.0, v46, 1.0
	v_mul_f32_e32 v48, v47, v38
	v_fma_f32 v49, -v34, v48, v47
	v_fmac_f32_e32 v48, v49, v38
	v_fma_f32 v34, -v34, v48, v47
	v_div_fmas_f32 v34, v34, v38, v48
	v_div_fixup_f32 v34, v34, v46, 1.0
	v_sub_f32_e32 v38, 1.0, v34
	v_fmac_f32_e32 v34, v30, v38
	v_cmp_gt_f32_e32 vcc, s11, v34
	s_nop 1
	v_cndmask_b32_e64 v30, 0, 32, vcc
	v_ldexp_f32 v30, v34, v30
	v_log_f32_e32 v30, v30
	s_nop 0
	v_mul_f32_e32 v34, 0x3f317217, v30
	v_fma_f32 v34, v30, s37, -v34
	v_fmac_f32_e32 v34, 0x3377d1cf, v30
	v_fmac_f32_e32 v34, 0x3f317217, v30
	v_cmp_lt_f32_e64 s[42:43], |v30|, s10
	s_nop 1
	v_cndmask_b32_e64 v30, v30, v34, s[42:43]
	v_cndmask_b32_e32 v34, 0, v225, vcc
	v_sub_f32_e32 v30, v30, v34
	v_sub_f32_e32 v34, v35, v39
	v_mul_f32_e32 v34, 0xbfb8aa3b, v34
	v_exp_f32_e32 v34, v34
	v_exp_f32_e32 v35, v31
	s_nop 0
	v_pk_add_f32 v[34:35], v[34:35], 1.0 op_sel_hi:[1,0]
	s_nop 0
	v_div_scale_f32 v31, s[0:1], v35, v35, 1.0
	v_rcp_f32_e32 v38, v31
	s_nop 0
	v_fma_f32 v39, -v31, v38, 1.0
	v_fmac_f32_e32 v38, v39, v38
	v_div_scale_f32 v39, vcc, 1.0, v35, 1.0
	v_mul_f32_e32 v46, v39, v38
	v_fma_f32 v47, -v31, v46, v39
	v_fmac_f32_e32 v46, v47, v38
	v_fma_f32 v31, -v31, v46, v39
	v_div_fmas_f32 v31, v31, v38, v46
	v_div_fixup_f32 v31, v31, v35, 1.0
	v_div_scale_f32 v35, s[0:1], v34, v34, 1.0
	v_rcp_f32_e32 v38, v35
	s_nop 0
	v_fma_f32 v39, -v35, v38, 1.0
	v_fmac_f32_e32 v38, v39, v38
	v_div_scale_f32 v39, vcc, 1.0, v34, 1.0
	v_mul_f32_e32 v46, v39, v38
	v_fma_f32 v47, -v35, v46, v39
	v_fmac_f32_e32 v46, v47, v38
	v_fma_f32 v35, -v35, v46, v39
	v_div_fmas_f32 v35, v35, v38, v46
	v_div_fixup_f32 v34, v35, v34, 1.0
	v_sub_f32_e32 v35, 1.0, v34
	v_fmac_f32_e32 v34, v31, v35
	v_cmp_gt_f32_e32 vcc, s11, v34
	v_exp_f32_e32 v35, v32
	s_nop 0
	v_cndmask_b32_e64 v31, 0, 32, vcc
	v_ldexp_f32 v31, v34, v31
	v_log_f32_e32 v31, v31
	s_nop 0
	v_mul_f32_e32 v34, 0x3f317217, v31
	v_fma_f32 v34, v31, s37, -v34
	v_fmac_f32_e32 v34, 0x3377d1cf, v31
	v_fmac_f32_e32 v34, 0x3f317217, v31
	v_cmp_lt_f32_e64 s[42:43], |v31|, s10
	s_nop 1
	v_cndmask_b32_e64 v31, v31, v34, s[42:43]
	v_cndmask_b32_e32 v34, 0, v225, vcc
	v_sub_f32_e32 v31, v31, v34
	v_sub_f32_e32 v34, v36, v40
	v_mul_f32_e32 v34, 0xbfb8aa3b, v34
	v_exp_f32_e32 v34, v34
	s_nop 0
	v_pk_add_f32 v[34:35], v[34:35], 1.0 op_sel_hi:[1,0]
	s_nop 0
	v_div_scale_f32 v32, s[0:1], v35, v35, 1.0
	v_rcp_f32_e32 v36, v32
	s_nop 0
	v_fma_f32 v38, -v32, v36, 1.0
	v_fmac_f32_e32 v36, v38, v36
	v_div_scale_f32 v38, vcc, 1.0, v35, 1.0
	v_mul_f32_e32 v39, v38, v36
	v_fma_f32 v40, -v32, v39, v38
	v_fmac_f32_e32 v39, v40, v36
	v_fma_f32 v32, -v32, v39, v38
	v_div_fmas_f32 v32, v32, v36, v39
	v_div_fixup_f32 v32, v32, v35, 1.0
	v_div_scale_f32 v35, s[0:1], v34, v34, 1.0
	v_rcp_f32_e32 v36, v35
	s_nop 0
	v_fma_f32 v38, -v35, v36, 1.0
	v_fmac_f32_e32 v36, v38, v36
	v_div_scale_f32 v38, vcc, 1.0, v34, 1.0
	v_mul_f32_e32 v39, v38, v36
	v_fma_f32 v40, -v35, v39, v38
	v_fmac_f32_e32 v39, v40, v36
	v_fma_f32 v35, -v35, v39, v38
	v_div_fmas_f32 v35, v35, v36, v39
	v_div_fixup_f32 v34, v35, v34, 1.0
	v_sub_f32_e32 v35, 1.0, v34
	v_fmac_f32_e32 v34, v32, v35
	v_cmp_gt_f32_e32 vcc, s11, v34
	v_exp_f32_e32 v35, v33
	s_nop 0
	v_cndmask_b32_e64 v32, 0, 32, vcc
	v_ldexp_f32 v32, v34, v32
	v_log_f32_e32 v32, v32
	s_nop 0
	v_mul_f32_e32 v34, 0x3f317217, v32
	v_fma_f32 v34, v32, s37, -v34
	v_fmac_f32_e32 v34, 0x3377d1cf, v32
	v_fmac_f32_e32 v34, 0x3f317217, v32
	v_cmp_lt_f32_e64 s[42:43], |v32|, s10
	s_nop 1
	v_cndmask_b32_e64 v32, v32, v34, s[42:43]
	v_cndmask_b32_e32 v34, 0, v225, vcc
	v_sub_f32_e32 v32, v32, v34
	v_sub_f32_e32 v34, v37, v41
	v_mul_f32_e32 v34, 0xbfb8aa3b, v34
	v_exp_f32_e32 v34, v34
	s_nop 0
	v_pk_add_f32 v[34:35], v[34:35], 1.0 op_sel_hi:[1,0]
	s_nop 0
	v_div_scale_f32 v33, s[0:1], v35, v35, 1.0
	v_rcp_f32_e32 v36, v33
	s_nop 0
	v_fma_f32 v37, -v33, v36, 1.0
	v_fmac_f32_e32 v36, v37, v36
	v_div_scale_f32 v37, vcc, 1.0, v35, 1.0
	v_mul_f32_e32 v38, v37, v36
	v_fma_f32 v39, -v33, v38, v37
	v_fmac_f32_e32 v38, v39, v36
	v_fma_f32 v33, -v33, v38, v37
	v_div_fmas_f32 v33, v33, v36, v38
	v_div_fixup_f32 v33, v33, v35, 1.0
	v_div_scale_f32 v35, s[0:1], v34, v34, 1.0
	v_rcp_f32_e32 v36, v35
	s_nop 0
	v_fma_f32 v37, -v35, v36, 1.0
	v_fmac_f32_e32 v36, v37, v36
	v_div_scale_f32 v37, vcc, 1.0, v34, 1.0
	v_mul_f32_e32 v38, v37, v36
	v_fma_f32 v39, -v35, v38, v37
	v_fmac_f32_e32 v38, v39, v36
	v_fma_f32 v35, -v35, v38, v37
	v_div_fmas_f32 v35, v35, v36, v38
	v_div_fixup_f32 v34, v35, v34, 1.0
	v_sub_f32_e32 v35, 1.0, v34
	v_fmac_f32_e32 v34, v33, v35
	v_cmp_gt_f32_e32 vcc, s11, v34
	s_nop 1
	v_cndmask_b32_e64 v33, 0, 32, vcc
	v_ldexp_f32 v33, v34, v33
	v_log_f32_e32 v33, v33
	s_nop 0
	v_mul_f32_e32 v34, 0x3f317217, v33
	v_fma_f32 v34, v33, s37, -v34
	v_fmac_f32_e32 v34, 0x3377d1cf, v33
	v_fmac_f32_e32 v34, 0x3f317217, v33
	v_cmp_lt_f32_e64 s[42:43], |v33|, s10
	s_nop 1
	v_cndmask_b32_e64 v33, v33, v34, s[42:43]
	v_cndmask_b32_e32 v34, 0, v225, vcc
	v_sub_f32_e32 v33, v33, v34

; DEV float sigm(float x) { return 1.f / (1.f + __expf(-x)); }
;   DEV void operator()(int m, int n, f32x4 v) {
;     ...
;     if (seg == 1 || seg == 2) {
;       const int dir = seg - 1;
; #pragma unroll
;       for (int r = 0; r < 4; r++) {
;         float lb = sigm(lbp[(2 + dir) * 1024 + c + r] - lbp[dir * 1024 + c + r]);
;         float ff = lb + (1.f - lb) * sigm(v[r]);
;         v[r] = __logf(ff);
;       }
;     }
.LBB0_548:
	s_addk_i32 s23, 0x430
	v_or_b32_e32 v18, s23, v79
	v_add_u32_e32 v20, 0xfffffc30, v78
	v_ashrrev_i32_e32 v19, 31, v18
	v_ashrrev_i32_e32 v21, 31, v20
	s_andn2_b64 vcc, exec, s[0:1]
	v_lshl_add_u64 v[26:27], v[18:19], 2, s[46:47]
	v_lshl_add_u64 v[28:29], v[20:21], 2, s[46:47]
	s_cbranch_vccnz .LBB0_550
	v_mul_f32_e32 v14, 0xbfb8aa3b, v14
	v_exp_f32_e32 v31, v14
	s_mov_b32 s11, 0x800000
	s_mov_b32 s10, 0x7f800000
	v_mul_f32_e32 v15, 0xbfb8aa3b, v15
	v_mul_f32_e32 v16, 0xbfb8aa3b, v16
	v_mul_f32_e32 v17, 0xbfb8aa3b, v17
	v_mov_b32_e32 v18, v244
	v_mov_b32_e32 v19, v245
	v_mov_b32_e32 v20, v246
	v_mov_b32_e32 v21, v247
	v_mov_b32_e32 v22, v248
	v_mov_b32_e32 v23, v249
	v_mov_b32_e32 v24, v192
	v_mov_b32_e32 v25, v193
	v_mov_b32_e32 v84, v18
	v_mov_b32_e32 v85, v19
	v_mov_b32_e32 v86, v20
	v_mov_b32_e32 v87, v21
	v_mov_b32_e32 v88, v22
	v_mov_b32_e32 v89, v23
	v_mov_b32_e32 v90, v24
	v_mov_b32_e32 v91, v25
	v_sub_f32_e32 v18, v18, v22
	v_mul_f32_e32 v18, 0xbfb8aa3b, v18
	v_exp_f32_e32 v30, v18
	s_nop 0
	v_pk_add_f32 v[30:31], v[30:31], 1.0 op_sel_hi:[1,0]
	s_nop 0
	v_div_scale_f32 v14, s[0:1], v31, v31, 1.0
	v_rcp_f32_e32 v18, v14
	s_nop 0
	v_fma_f32 v22, -v14, v18, 1.0
	v_fmac_f32_e32 v18, v22, v18
	v_div_scale_f32 v22, vcc, 1.0, v31, 1.0
	v_mul_f32_e32 v32, v22, v18
	v_fma_f32 v33, -v14, v32, v22
	v_fmac_f32_e32 v32, v33, v18
	v_fma_f32 v14, -v14, v32, v22
	v_div_fmas_f32 v14, v14, v18, v32
	v_div_scale_f32 v18, s[0:1], v30, v30, 1.0
	v_rcp_f32_e32 v22, v18
	v_div_fixup_f32 v14, v14, v31, 1.0
	v_fma_f32 v31, -v18, v22, 1.0
	v_fmac_f32_e32 v22, v31, v22
	v_div_scale_f32 v31, vcc, 1.0, v30, 1.0
	v_mul_f32_e32 v32, v31, v22
	v_fma_f32 v33, -v18, v32, v31
	v_fmac_f32_e32 v32, v33, v22
	v_fma_f32 v18, -v18, v32, v31
	v_div_fmas_f32 v18, v18, v22, v32
	v_div_fixup_f32 v18, v18, v30, 1.0
	v_sub_f32_e32 v22, 1.0, v18
	v_fmac_f32_e32 v18, v14, v22
	v_cmp_gt_f32_e32 vcc, s11, v18
	s_nop 1
	v_cndmask_b32_e64 v14, 0, 32, vcc
	v_ldexp_f32 v14, v18, v14
	v_log_f32_e32 v14, v14
	s_nop 0
	v_mul_f32_e32 v18, 0x3f317217, v14
	v_fma_f32 v18, v14, s37, -v18
	v_fmac_f32_e32 v18, 0x3377d1cf, v14
	v_fmac_f32_e32 v18, 0x3f317217, v14
	v_cmp_lt_f32_e64 s[42:43], |v14|, s10
	s_nop 1
	v_cndmask_b32_e64 v14, v14, v18, s[42:43]
	v_cndmask_b32_e32 v18, 0, v225, vcc
	v_sub_f32_e32 v14, v14, v18
	v_sub_f32_e32 v18, v19, v23
	v_mul_f32_e32 v18, 0xbfb8aa3b, v18
	v_exp_f32_e32 v18, v18
	v_exp_f32_e32 v19, v15
	s_nop 0
	v_pk_add_f32 v[18:19], v[18:19], 1.0 op_sel_hi:[1,0]
	s_nop 0
	v_div_scale_f32 v15, s[0:1], v19, v19, 1.0
	v_rcp_f32_e32 v22, v15
	s_nop 0
	v_fma_f32 v23, -v15, v22, 1.0
	v_fmac_f32_e32 v22, v23, v22
	v_div_scale_f32 v23, vcc, 1.0, v19, 1.0
	v_mul_f32_e32 v30, v23, v22
	v_fma_f32 v31, -v15, v30, v23
	v_fmac_f32_e32 v30, v31, v22
	v_fma_f32 v15, -v15, v30, v23
	v_div_fmas_f32 v15, v15, v22, v30
	v_div_fixup_f32 v15, v15, v19, 1.0
	v_div_scale_f32 v19, s[0:1], v18, v18, 1.0
	v_rcp_f32_e32 v22, v19
	s_nop 0
	v_fma_f32 v23, -v19, v22, 1.0
	v_fmac_f32_e32 v22, v23, v22
	v_div_scale_f32 v23, vcc, 1.0, v18, 1.0
	v_mul_f32_e32 v30, v23, v22
	v_fma_f32 v31, -v19, v30, v23
	v_fmac_f32_e32 v30, v31, v22
	v_fma_f32 v19, -v19, v30, v23
	v_div_fmas_f32 v19, v19, v22, v30
	v_div_fixup_f32 v18, v19, v18, 1.0
	v_sub_f32_e32 v19, 1.0, v18
	v_fmac_f32_e32 v18, v15, v19
	v_cmp_gt_f32_e32 vcc, s11, v18
	v_exp_f32_e32 v19, v16
	s_nop 0
	v_cndmask_b32_e64 v15, 0, 32, vcc
	v_ldexp_f32 v15, v18, v15
	v_log_f32_e32 v15, v15
	s_nop 0
	v_mul_f32_e32 v18, 0x3f317217, v15
	v_fma_f32 v18, v15, s37, -v18
	v_fmac_f32_e32 v18, 0x3377d1cf, v15
	v_fmac_f32_e32 v18, 0x3f317217, v15
	v_cmp_lt_f32_e64 s[42:43], |v15|, s10
	s_nop 1
	v_cndmask_b32_e64 v15, v15, v18, s[42:43]
	v_cndmask_b32_e32 v18, 0, v225, vcc
	v_sub_f32_e32 v15, v15, v18
	v_sub_f32_e32 v18, v20, v24
	v_mul_f32_e32 v18, 0xbfb8aa3b, v18
	v_exp_f32_e32 v18, v18
	s_nop 0
	v_pk_add_f32 v[18:19], v[18:19], 1.0 op_sel_hi:[1,0]
	s_nop 0
	v_div_scale_f32 v16, s[0:1], v19, v19, 1.0
	v_rcp_f32_e32 v20, v16
	s_nop 0
	v_fma_f32 v22, -v16, v20, 1.0
	v_fmac_f32_e32 v20, v22, v20
	v_div_scale_f32 v22, vcc, 1.0, v19, 1.0
	v_mul_f32_e32 v23, v22, v20
	v_fma_f32 v24, -v16, v23, v22
	v_fmac_f32_e32 v23, v24, v20
	v_fma_f32 v16, -v16, v23, v22
	v_div_fmas_f32 v16, v16, v20, v23
	v_div_fixup_f32 v16, v16, v19, 1.0
	v_div_scale_f32 v19, s[0:1], v18, v18, 1.0
	v_rcp_f32_e32 v20, v19
	s_nop 0
	v_fma_f32 v22, -v19, v20, 1.0
	v_fmac_f32_e32 v20, v22, v20
	v_div_scale_f32 v22, vcc, 1.0, v18, 1.0
	v_mul_f32_e32 v23, v22, v20
	v_fma_f32 v24, -v19, v23, v22
	v_fmac_f32_e32 v23, v24, v20
	v_fma_f32 v19, -v19, v23, v22
	v_div_fmas_f32 v19, v19, v20, v23
	v_div_fixup_f32 v18, v19, v18, 1.0
	v_sub_f32_e32 v19, 1.0, v18
	v_fmac_f32_e32 v18, v16, v19
	v_cmp_gt_f32_e32 vcc, s11, v18
	v_exp_f32_e32 v19, v17
	s_nop 0
	v_cndmask_b32_e64 v16, 0, 32, vcc
	v_ldexp_f32 v16, v18, v16
	v_log_f32_e32 v16, v16
	s_nop 0
	v_mul_f32_e32 v18, 0x3f317217, v16
	v_fma_f32 v18, v16, s37, -v18
	v_fmac_f32_e32 v18, 0x3377d1cf, v16
	v_fmac_f32_e32 v18, 0x3f317217, v16
	v_cmp_lt_f32_e64 s[42:43], |v16|, s10
	s_nop 1
	v_cndmask_b32_e64 v16, v16, v18, s[42:43]
	v_cndmask_b32_e32 v18, 0, v225, vcc
	v_sub_f32_e32 v16, v16, v18
	v_sub_f32_e32 v18, v21, v25
	v_mul_f32_e32 v18, 0xbfb8aa3b, v18
	v_exp_f32_e32 v18, v18
	s_nop 0
	v_pk_add_f32 v[18:19], v[18:19], 1.0 op_sel_hi:[1,0]
	s_nop 0
	v_div_scale_f32 v17, s[0:1], v19, v19, 1.0
	v_rcp_f32_e32 v20, v17
	s_nop 0
	v_fma_f32 v21, -v17, v20, 1.0
	v_fmac_f32_e32 v20, v21, v20
	v_div_scale_f32 v21, vcc, 1.0, v19, 1.0
	v_mul_f32_e32 v22, v21, v20
	v_fma_f32 v23, -v17, v22, v21
	v_fmac_f32_e32 v22, v23, v20
	v_fma_f32 v17, -v17, v22, v21
	v_div_fmas_f32 v17, v17, v20, v22
	v_div_fixup_f32 v17, v17, v19, 1.0
	v_div_scale_f32 v19, s[0:1], v18, v18, 1.0
	v_rcp_f32_e32 v20, v19
	s_nop 0
	v_fma_f32 v21, -v19, v20, 1.0
	v_fmac_f32_e32 v20, v21, v20
	v_div_scale_f32 v21, vcc, 1.0, v18, 1.0
	v_mul_f32_e32 v22, v21, v20
	v_fma_f32 v23, -v19, v22, v21
	v_fmac_f32_e32 v22, v23, v20
	v_fma_f32 v19, -v19, v22, v21
	v_div_fmas_f32 v19, v19, v20, v22
	v_div_fixup_f32 v18, v19, v18, 1.0
	v_sub_f32_e32 v19, 1.0, v18
	v_fmac_f32_e32 v18, v17, v19
	v_cmp_gt_f32_e32 vcc, s11, v18
	s_nop 1
	v_cndmask_b32_e64 v17, 0, 32, vcc
	v_ldexp_f32 v17, v18, v17
	v_log_f32_e32 v17, v17
	s_nop 0
	v_mul_f32_e32 v18, 0x3f317217, v17
	v_fma_f32 v18, v17, s37, -v18
	v_fmac_f32_e32 v18, 0x3377d1cf, v17
	v_fmac_f32_e32 v18, 0x3f317217, v17
	v_cmp_lt_f32_e64 s[42:43], |v17|, s10
	s_nop 1
	v_cndmask_b32_e64 v17, v17, v18, s[42:43]
	v_cndmask_b32_e32 v18, 0, v225, vcc
	v_sub_f32_e32 v17, v17, v18
